# v11 plus the same K-tile bank-conflict swizzle fix in the sample attention unit
# baseline (speedup 1.0000x reference)
.LBB0_734:
	global_load_dwordx4 v[2:5], v[68:69], off
	global_load_dwordx4 v[6:9], v[68:69], off offset:32
	global_load_dwordx4 v[10:13], v[68:69], off offset:64
	global_load_dwordx4 v[72:75], v[68:69], off offset:96
	global_load_dwordx4 v[80:83], v[68:69], off offset:192
	v_add_u32_e32 v84, s8, v71
	s_mov_b64 s[10:11], 0x10000
	s_add_i32 s8, s8, 64
	s_cmpk_lg_i32 s8, 0x200
	s_waitcnt vmcnt(4)
	v_mfma_f32_32x32x16_bf16 v[16:31], v[32:35], v[2:5], 0
	global_load_dwordx4 v[2:5], v[68:69], off offset:128
	global_load_dwordx4 v[76:79], v[68:69], off offset:160
	s_waitcnt vmcnt(5)
	v_mfma_f32_32x32x16_bf16 v[16:31], v[36:39], v[6:9], v[16:31]
	s_waitcnt vmcnt(4)
	v_mfma_f32_32x32x16_bf16 v[16:31], v[40:43], v[10:13], v[16:31]
	s_waitcnt vmcnt(3)
	v_mfma_f32_32x32x16_bf16 v[16:31], v[44:47], v[72:75], v[16:31]
	global_load_dwordx4 v[72:75], v[68:69], off offset:224
	v_lshl_add_u64 v[68:69], v[68:69], 0, s[10:11]
	s_waitcnt vmcnt(2)
	v_mfma_f32_32x32x16_bf16 v[16:31], v[48:51], v[2:5], v[16:31]
	s_waitcnt vmcnt(1)
	v_mfma_f32_32x32x16_bf16 v[16:31], v[52:55], v[76:79], v[16:31]
	v_mfma_f32_32x32x16_bf16 v[16:31], v[56:59], v[80:83], v[16:31]
	s_waitcnt vmcnt(0)
	v_mfma_f32_32x32x16_bf16 v[16:31], v[60:63], v[72:75], v[16:31]
	s_nop 11
	v_cvt_pk_bf16_f32 v16, v16, s0
	v_cvt_pk_bf16_f32 v17, v17, s0
	v_cvt_pk_bf16_f32 v18, v18, s0
	v_cvt_pk_bf16_f32 v19, v19, s0
	v_cvt_pk_bf16_f32 v20, v20, s0
	v_cvt_pk_bf16_f32 v21, v21, s0
	v_cvt_pk_bf16_f32 v22, v22, s0
	v_cvt_pk_bf16_f32 v23, v23, s0
	ds_write_b16 v84, v16
	ds_write_b16 v84, v17 offset:528
	ds_write_b16 v84, v18 offset:1056
	ds_write_b16 v84, v19 offset:1584
	ds_write_b16 v84, v20 offset:4224
	ds_write_b16 v84, v21 offset:4752
	ds_write_b16 v84, v22 offset:5280
	ds_write_b16 v84, v23 offset:5808
	s_cbranch_scc1 .LBB0_734
	v_lshlrev_b32_e32 v16, 1, v70
	v_and_b32_e32 v153, 6, v16
	v_lshrrev_b32_e32 v16, 4, v150
	v_or_b32_e32 v176, v153, v16
	v_mul_u32_u24_e32 v16, 0xc0, v176
	v_lshlrev_b32_e32 v16, 1, v16
	v_mov_b32_e32 v17, v0
	s_and_b32 s60, s90, 3
	v_lshl_add_u64 v[16:17], v[66:67], 0, v[16:17]
	v_lshlrev_b32_e32 v18, 1, v64
	v_mov_b32_e32 v19, v0
	v_lshl_add_u64 v[16:17], v[16:17], 0, v[18:19]
	s_cmp_eq_u32 s60, 3
	s_waitcnt lgkmcnt(0)
	s_barrier
	global_load_dwordx4 v[112:115], v[16:17], off offset:256
	global_load_dwordx4 v[116:119], v[16:17], off offset:288
	global_load_dwordx4 v[120:123], v[16:17], off offset:320
	global_load_dwordx4 v[124:127], v[16:17], off offset:352
	v_lshlrev_b32_e32 v17, 4, v65
	s_cselect_b32 s91, 17, 16
	s_ashr_i32 s21, s20, 31
	v_lshlrev_b32_e32 v16, 3, v65
	v_and_b32_e32 v17, 0xc0, v17
	v_lshlrev_b32_e32 v18, 1, v65
	s_lshl_b64 s[24:25], s[20:21], 12
	s_lshl_b32 s8, s60, 10
	v_and_or_b32 v17, v16, 24, v17
	v_and_b32_e32 v18, 32, v18
	v_and_b32_e32 v16, 0x100, v16
	v_ashrrev_i32_e32 v156, 5, v151
	s_or_b32 s24, s24, s8
	v_or3_b32 v26, v17, v18, v16
	v_lshlrev_b32_e32 v29, 4, v151
	v_lshlrev_b32_e32 v17, 3, v156
	s_add_u32 s8, s24, 0x8200
	v_add_u32_e32 v160, 16, v156
	v_and_b32_e32 v16, 0x1f0, v29
	v_and_b32_e32 v30, 0x70, v17
	s_addc_u32 s9, s25, 0
	v_mov_b32_e32 v17, v0
	v_ashrrev_i32_e32 v157, 31, v156
	v_ashrrev_i32_e32 v161, 31, v160
	v_lshl_add_u64 v[158:159], s[54:55], 0, v[16:17]
	v_lshl_add_u64 v[16:17], s[8:9], 0, v[156:157]
	v_lshl_add_u64 v[20:21], s[8:9], 0, v[160:161]
	v_lshlrev_b64 v[16:17], 9, v[16:17]
	v_lshlrev_b64 v[20:21], 9, v[20:21]
	v_add_u32_e32 v162, 32, v156
	v_add_u32_e32 v164, 48, v156
	v_lshl_add_u64 v[16:17], v[158:159], 0, v[16:17]
	v_lshl_add_u64 v[20:21], v[158:159], 0, v[20:21]
	v_ashrrev_i32_e32 v163, 31, v162
	v_ashrrev_i32_e32 v165, 31, v164
	global_load_dwordx4 v[132:135], v[16:17], off
	global_load_dwordx4 v[128:131], v[20:21], off
	v_lshl_add_u64 v[16:17], s[8:9], 0, v[162:163]
	v_lshl_add_u64 v[20:21], s[8:9], 0, v[164:165]
	v_ashrrev_i32_e32 v154, 3, v151
	s_lshl_b64 s[10:11], s[24:25], 7
	v_lshlrev_b64 v[16:17], 9, v[16:17]
	v_lshlrev_b64 v[20:21], 9, v[20:21]
	v_lshl_add_u64 v[16:17], v[158:159], 0, v[16:17]
	v_lshl_add_u64 v[20:21], v[158:159], 0, v[20:21]
	s_add_u32 s10, s71, s10
	v_ashrrev_i32_e32 v155, 31, v154
	v_and_b32_e32 v27, 7, v151
	global_load_dwordx4 v[136:139], v[16:17], off
	global_load_dwordx4 v[140:143], v[20:21], off
	s_addc_u32 s11, s72, s11
	v_lshlrev_b64 v[16:17], 7, v[154:155]
	v_lshl_add_u64 v[20:21], s[8:9], 0, v[154:155]
	v_lshlrev_b32_e32 v18, 4, v27
	v_lshl_add_u64 v[16:17], s[10:11], 0, v[16:17]
	v_lshlrev_b64 v[20:21], 5, v[20:21]
	v_lshl_add_u64 v[16:17], v[16:17], 0, v[18:19]
	v_lshl_add_u64 v[20:21], s[56:57], 0, v[20:21]
	v_lshlrev_b32_e32 v22, 2, v27
	v_mov_b32_e32 v23, v0
	v_lshl_add_u64 v[20:21], v[20:21], 0, v[22:23]
	global_load_dwordx4 v[144:147], v[16:17], off
	global_load_dword v173, v[20:21], off
	v_and_b32_e32 v19, 0xfffff0, v156
	v_lshlrev_b32_e32 v20, 1, v156
	v_and_or_b32 v19, v20, 8, v19
	v_lshrrev_b32_e32 v19, 1, v19
	v_lshrrev_b32_e32 v21, 2, v151
	v_lshlrev_b32_e32 v16, 10, v151
	v_lshrrev_b32_e32 v20, 1, v156
	v_and_or_b32 v19, v21, 3, v19
	v_and_b32_e32 v21, 3, v156
	v_and_b32_e32 v16, 0x4000, v16
	v_and_or_b32 v20, v20, 4, v21
	v_add_u32_e32 v16, s83, v16
	v_lshlrev_b32_e32 v19, 9, v19
	v_lshlrev_b32_e32 v20, 6, v20
	v_add3_u32 v19, v16, v19, v20
	v_lshlrev_b32_e32 v20, 3, v154
	v_and_b32_e32 v20, 0x70, v20
	s_movk_i32 s8, 0x200
	v_bitop3_b32 v18, v18, v20, s8 bitop3:0x36
	s_lshl_b64 s[8:9], s[22:23], 7
	v_mul_lo_u32 v16, v154, s84
	s_add_u32 s92, s67, s8
	v_ashrrev_i32_e32 v174, 8, v151
	v_add_u32_e32 v33, s86, v16
	v_mul_u32_u24_e32 v16, 0x108, v148
	s_addc_u32 s93, s68, s9
	s_lshl_b64 s[26:27], s[20:21], 19
	s_lshl_b32 s28, s60, 17
	v_lshlrev_b32_e32 v25, 14, v174
	v_add_lshl_u32 v34, v64, v16, 1
	v_and_b32_e32 v16, 32, v151
	s_or_b32 s26, s26, s28
	v_and_b32_e32 v24, 0x3fffffc0, v151
	v_mul_lo_u32 v28, v156, s84
	v_bitop3_b32 v17, v29, v30, s85 bitop3:0x6c
	v_lshlrev_b32_e32 v21, 3, v151
	v_and_b32_e32 v21, 0x70, v21
	v_or_b32_e32 v30, 32, v152
	v_or_b32_e32 v31, 64, v152
	v_or_b32_e32 v32, 0x60, v152
	v_lshlrev_b32_e32 v35, 2, v16
	v_add3_u32 v178, v25, s83, v26
	v_lshlrev_b32_e32 v25, 2, v176
	s_add_u32 s94, s73, s26
	v_mov_b32_e32 v14, v0
	v_mov_b32_e32 v15, v0
	v_mul_u32_u24_e32 v20, 0x280, v150
	v_add_u32_e32 v28, s86, v28
	v_and_b32_e32 v29, 48, v29
	v_lshl_add_u32 v177, v24, 2, s88
	v_lshlrev_b32_e32 v16, 3, v27
	v_mad_u32_u24 v24, v176, s82, 0
	v_add3_u32 v179, s87, v35, v25
	v_lshl_add_u64 v[168:169], s[56:57], 0, v[22:23]
	v_xad_u32 v22, v152, v21, s86
	v_xad_u32 v23, v30, v21, s86
	v_xad_u32 v25, v31, v21, s86
	v_xad_u32 v21, v32, v21, s86
	s_addc_u32 s95, s74, s27
	v_mov_b32_e32 v1, v0
	v_mov_b32_e32 v2, v0
	v_mov_b32_e32 v3, v0
	v_mov_b32_e32 v4, v0
	v_mov_b32_e32 v5, v0
	v_mov_b32_e32 v6, v0
	v_mov_b32_e32 v7, v0
	v_mov_b32_e32 v8, v0
	v_mov_b32_e32 v9, v0
	v_mov_b32_e32 v10, v0
	v_mov_b32_e32 v11, v0
	v_mov_b32_e32 v12, v0
	v_mov_b32_e32 v13, v0
	v_cmp_gt_u32_e64 s[8:9], 32, v65
	s_add_u32 s96, s24, 0x8240
	v_add_u32_e32 v184, v28, v17
	v_add_u32_e32 v185, v19, v29
	v_add_u32_e32 v186, v33, v18
	v_lshlrev_b32_e32 v172, 1, v16
	v_add_u32_e32 v187, v22, v20
	v_add_u32_e32 v188, v24, v34
	v_add_u32_e32 v189, v23, v20
	v_add_u32_e32 v190, v25, v20
	v_add_u32_e32 v191, v21, v20
	v_mov_b64_e32 v[30:31], v[14:15]
	v_mov_b64_e32 v[46:47], v[14:15]
	v_mov_b64_e32 v[62:63], v[14:15]
	v_mov_b64_e32 v[78:79], v[14:15]
	s_mov_b32 s90, 1
	v_lshlrev_b64 v[166:167], 6, v[154:155]
	v_lshl_add_u32 v182, v151, 2, s87
	v_cmp_gt_i32_e64 s[10:11], 16, v154
	v_lshl_add_u32 v183, v150, 2, v177
	v_cmp_gt_i32_e64 s[12:13], 16, v156
	v_cmp_gt_i32_e64 s[14:15], 0, v156
	v_cmp_gt_i32_e64 s[16:17], -16, v156
	v_cmp_gt_i32_e64 s[18:19], s89, v156
	s_addc_u32 s97, s25, 0
	s_lshl_b32 s66, s91, 13
	v_mov_b32_e32 v192, 0
	v_mov_b32_e32 v170, 0xf149f2ca
	s_mov_b64 s[24:25], 0
	v_mov_b64_e32 v[28:29], v[12:13]
	v_mov_b64_e32 v[26:27], v[10:11]
	v_mov_b64_e32 v[24:25], v[8:9]
	v_mov_b64_e32 v[22:23], v[6:7]
	v_mov_b64_e32 v[20:21], v[4:5]
	v_mov_b64_e32 v[18:19], v[2:3]
	v_mov_b64_e32 v[16:17], v[0:1]
	v_mov_b64_e32 v[44:45], v[12:13]
	v_mov_b64_e32 v[42:43], v[10:11]
	v_mov_b64_e32 v[40:41], v[8:9]
	v_mov_b64_e32 v[38:39], v[6:7]
	v_mov_b64_e32 v[36:37], v[4:5]
	v_mov_b64_e32 v[34:35], v[2:3]
	v_mov_b64_e32 v[32:33], v[0:1]
	v_mov_b64_e32 v[60:61], v[12:13]
	v_mov_b64_e32 v[58:59], v[10:11]
	v_mov_b64_e32 v[56:57], v[8:9]
	v_mov_b64_e32 v[54:55], v[6:7]
	v_mov_b64_e32 v[52:53], v[4:5]
	v_mov_b64_e32 v[50:51], v[2:3]
	v_mov_b64_e32 v[48:49], v[0:1]
	v_mov_b64_e32 v[76:77], v[12:13]
	v_mov_b64_e32 v[74:75], v[10:11]
	v_mov_b64_e32 v[72:73], v[8:9]
	v_mov_b64_e32 v[70:71], v[6:7]
	v_mov_b64_e32 v[68:69], v[4:5]
	v_mov_b64_e32 v[66:67], v[2:3]
	v_mov_b64_e32 v[64:65], v[0:1]
